# DSA order P3a|P4a|P3b|(P5a waves0-3 || P4b waves4-7)|P5b with per-XCD dynamic attention work list; plus cg-sync/final-barrier removal, FF1 epilogue hoist, 1us GEMM start stagger, indexer relu fold
# speedup vs baseline: 1.0199x; 1.0154x over previous
; #define LAS __attribute__((address_space(3)))
; __device__ __forceinline__ void attend_one(unsigned char* ws, LAS unsigned char* lds, int wave, int bb, int t, int kvh, int lane) {
;     asm volatile("" : "+v"(lane));
;     const int n = lane & 15, g = lane >> 4;
;     const bf16_t* Kb = (const bf16_t*)(ws + WS_DK) + (size_t)(bb * 4 + kvh) * 8192 * 128;
;     const bf16_t* Vb = (const bf16_t*)(ws + WS_DV) + (size_t)(bb * 4 + kvh) * 8192 * 128;
;     bf16_t* qrow = (bf16_t*)(ws + WS_DQ) + (size_t)(bb * 8192 + t) * 2048 + kvh * 512;
;     const unsigned short* ix = (const unsigned short*)(ws + WS_IDX) + (size_t)(bb * 8192 + t) * 256;
;     const int cnt = t < 255 ? t + 1 : 256;
;     LAS unsigned* li = (LAS unsigned*)(lds + wave * 1024);
;     { const u32x2 iw = *(const u32x2*)(ix + lane * 4); *(LAS u32x4*)(li + lane * 4) = (u32x4){(iw.x & 0xffffu) << 8, (iw.x >> 16) << 8, (iw.y & 0xffffu) << 8, (iw.y >> 16) << 8}; }
;     bf16x8 qf[4];
; #pragma unroll
;     for (int kk = 0; kk < 4; ++kk) { qf[kk] = (bf16x8){0, 0, 0, 0, 0, 0, 0, 0}; if (n < 4) qf[kk] = *(const bf16x8*)(qrow + n * 128 + kk * 32 + g * 8); }
.LBB0_2929:
	s_mov_b32 s90, 0
	s_branch .LBB0_2955
.Lp5a_begin:
	s_cmp_gt_i32 s43, 5
	s_cselect_b64 s[4:5], -1, 0
	s_cmp_lt_i32 s42, 6
	s_cselect_b64 s[0:1], -1, 0
	s_and_b64 s[0:1], s[0:1], s[4:5]
	s_andn2_b64 vcc, exec, s[0:1]
	s_cbranch_vccnz .Lp5a_exit
	v_readlane_b32 s0, v255, 0
	v_readlane_b32 s1, v255, 1
	s_cmpk_lg_i32 s44, 0x100
	s_mov_b64 s[10:11], 0
	s_waitcnt vmcnt(0)
	v_mbcnt_lo_u32_b32 v164, -1, 0
	v_mbcnt_hi_u32_b32 v164, -1, v164
	s_cbranch_scc1 .LBB0_2934
	s_add_i32 s0, 0, 0x20000
	v_mov_b32_e32 v0, s0
	ds_read_b32 v0, v0
	s_waitcnt lgkmcnt(0)
	v_cmp_ne_u32_e32 vcc, 32, v0
	s_cbranch_vccnz .LBB0_2934
	s_add_i32 s0, 0, 0x20004
	v_mov_b32_e32 v0, s0
	ds_read_b32 v0, v0
	s_waitcnt lgkmcnt(0)
	v_cmp_ne_u32_e32 vcc, 8, v0
	s_cbranch_vccnz .LBB0_2934
	s_add_i32 s0, 0, 0x2000c
	v_mov_b32_e32 v0, s0
	ds_read_b32 v0, v0
	s_waitcnt lgkmcnt(0)
	v_readfirstlane_b32 s0, v0
	s_cmp_lt_u32 s0, 8
	s_cselect_b64 s[10:11], -1, 0
.LBB0_2934:
	s_add_i32 s0, 0, 0x2000c
	v_mov_b32_e32 v0, s0
	ds_read_b32 v0, v0
	s_lshl_b32 s0, s2, 3
	s_add_i32 s4, 0, 0x20008
	v_readlane_b32 s1, v255, 3
	s_add_i32 s0, s1, s0
	s_waitcnt lgkmcnt(0)
	v_readfirstlane_b32 s1, v0
	v_mov_b32_e32 v0, s4
	ds_read_b32 v0, v0
	s_cmp_lt_i32 s0, 0x8000
	s_cselect_b64 s[4:5], -1, 0
	s_or_b64 s[4:5], s[10:11], s[4:5]
	s_mov_b32 s3, 0
	s_andn2_b64 vcc, exec, s[4:5]
	s_waitcnt lgkmcnt(0)
	v_readfirstlane_b32 s4, v0
	s_cbranch_vccnz .Lp5a_exit
	v_readlane_b32 s7, v255, 3
	s_bfe_u32 s5, s1, 0x10002
	s_lshl_b32 s4, s4, 4
	s_lshl_b32 s6, s7, 1
	s_add_u32 s16, s40, 0x12800000
	s_addc_u32 s17, s41, 0
	s_add_u32 s18, s40, 0xd800000
	s_addc_u32 s19, s41, 0
	s_add_u32 s20, s40, 0xe00000
	s_addc_u32 s21, s41, 0
	s_lshl_b32 s7, s7, 10
	s_add_i32 s22, s7, 0x4000
	s_add_u32 s23, s40, 0x11800000
	s_addc_u32 s24, s41, 0
	s_add_i32 s4, s4, s6
	s_mov_b64 s[100:101], exec
	s_lshl_b32 s98, s1, 6
	s_addk_i32 s98, 0x3800
	s_add_u32 s98, s40, s98
	s_addc_u32 s99, s41, 0
	v_mov_b32_e32 v251, 0
	v_mov_b32_e32 v252, 1
	s_mov_b64 exec, 1
	global_atomic_add v250, v251, v252, s[98:99] sc0
	s_mov_b64 exec, s[100:101]
	s_waitcnt vmcnt(0)
	v_readfirstlane_b32 s100, v250
	s_bfe_u32 s101, s1, 0x10002
	s_lshl_b32 s25, s100, 1
	s_or_b32 s25, s25, s101
	v_mov_b32_e32 v161, 0
	s_mov_b32 s26, 0xff61b1e6
	s_mov_b32 s27, 0x5040100
	s_mov_b32 s28, 0x7060302
	v_mov_b32_e32 v165, 8
	v_mov_b32_e32 v166, 0xff61b1e6
	s_branch .LBB0_2937
.LBB0_2936:
	s_or_b64 exec, exec, s[4:5]
	s_add_i32 s0, s0, s87
	s_add_i32 s6, s3, 1
	s_cmp_lt_u32 s100, 0x1000
	s_cselect_b64 s[4:5], -1, 0
	s_cmp_lt_i32 s0, 0x8000
	v_cndmask_b32_e64 v0, 0, 1, s[4:5]
	s_cselect_b64 s[4:5], -1, 0
	v_cndmask_b32_e64 v1, 0, 1, s[4:5]
	v_cndmask_b32_e64 v0, v1, v0, s[10:11]
	v_and_b32_e32 v0, 1, v0
	v_cmp_eq_u32_e32 vcc, 1, v0
	s_bfe_u32 s101, s1, 0x10002
	s_lshl_b32 s25, s100, 1
	s_or_b32 s25, s25, s101
	s_mov_b32 s3, s6
	s_cbranch_vccz .Lp5a_exit
.LBB0_2937:
	s_mov_b64 exec, 1
	global_atomic_add v250, v251, v252, s[98:99] sc0
	s_mov_b64 exec, -1
	s_ashr_i32 s6, s0, 2
	s_and_b64 s[4:5], s[10:11], exec
	s_cselect_b32 s5, s1, s0
	s_cselect_b32 s4, s25, s6
	s_and_b32 s8, s5, 3
	s_ashr_i32 s5, s4, 31
	s_lshl_b64 s[6:7], s[4:5], 12
	s_add_u32 s6, s18, s6
	s_addc_u32 s7, s19, s7
	s_lshl_b32 s9, s8, 10
	s_add_u32 s12, s6, s9
	v_mov_b32_e32 v167, v164
	s_addc_u32 s13, s7, 0
	s_lshl_b64 s[6:7], s[4:5], 9
	s_add_u32 s6, s20, s6
	v_lshlrev_b32_e32 v162, 2, v167
	s_addc_u32 s7, s21, s7
	v_ashrrev_i32_e32 v163, 31, v162
	v_lshl_add_u64 v[0:1], v[162:163], 1, s[6:7]
	global_load_dwordx2 v[6:7], v[0:1], off
	v_and_b32_e32 v18, 15, v167
	v_ashrrev_i32_e32 v168, 4, v167
	v_lshlrev_b32_e32 v160, 8, v18
	v_lshlrev_b32_e32 v4, 3, v168
	v_ashrrev_i32_e32 v5, 31, v4
	v_lshl_add_u64 v[8:9], s[12:13], 0, v[160:161]
	v_lshl_add_u64 v[16:17], v[4:5], 1, v[8:9]
	v_lshl_add_u32 v3, v167, 4, s22
	v_mov_b32_e32 v0, 0
	v_mov_b32_e32 v1, 0
	v_mov_b32_e32 v2, 0
	v_cmp_gt_u32_e32 vcc, 4, v18
	s_waitcnt vmcnt(0)
	v_readfirstlane_b32 s100, v250
	v_lshlrev_b32_e32 v4, 8, v6
	v_lshlrev_b32_sdwa v5, v165, v6 dst_sel:DWORD dst_unused:UNUSED_PAD src0_sel:DWORD src1_sel:WORD_1
	v_lshlrev_b32_e32 v6, 8, v7
	v_lshlrev_b32_sdwa v7, v165, v7 dst_sel:DWORD dst_unused:UNUSED_PAD src0_sel:DWORD src1_sel:WORD_1
	v_and_b32_e32 v4, 0xffff00, v4
	v_and_b32_e32 v6, 0xffff00, v6
	ds_write_b128 v3, v[4:7]
	v_mov_b32_e32 v3, 0
	s_and_saveexec_b64 s[6:7], vcc
	s_cbranch_execz .LBB0_2939
	global_load_dwordx4 v[0:3], v[16:17], off

; #define PHASE_END_NOBAR } ++ph; __syncthreads();
; #define PHASE_END } ++ph; if (ph > ph_lo && ph < ph_hi) { grid_bar((unsigned*)ws, bst, (unsigned)G, wave); }
; __global__ void __launch_bounds__(512, 2) hybrid_fwd(Args A0) {
;     ...
;     DSA_ROUND(0, PHASE_END_NOBAR)
;     DSA_ROUND(1, PHASE_END)
.Lp5a_exit:
	s_and_b64 vcc, exec, s[88:89]
	s_cbranch_vccnz .LBB0_4694
	s_mov_b32 s90, 1
	s_waitcnt lgkmcnt(0)
	s_barrier
	s_branch .LBB0_3029

; #define LAS __attribute__((address_space(3)))
; __device__ __forceinline__ void select_one(const unsigned short* sc, int t, unsigned short* idx, int lane, LAS unsigned short* li, LAS unsigned* hist) {
;     if (t < 256) {
; #pragma unroll
;         for (int j = 0; j < 4; ++j) { const int i = j * 64 + lane; idx[i] = (unsigned short)(i <= t ? i : 0); }
;         return;
;     }
;     unsigned key[128];
;     const int ngrp = (t >> 9) + 1;
;     u32x4 wv[16];
; #pragma unroll
;     for (int gI = 0; gI < 16; ++gI) wv[gI] = *(const u32x4*)(sc + gI * 512 + lane * 8);
; #pragma unroll
;     for (int gI = 0; gI < 16; ++gI) {
;         const int s0 = gI * 512 + lane * 8; const u32x4 w = wv[gI];
; #pragma unroll
;         for (int q = 0; q < 8; ++q) { const unsigned wd = w[q >> 1]; const unsigned h = (q & 1) ? (wd >> 16) : (wd & 0xffffu);
;             const unsigned k = (h & 0x8000u) ? (~h & 0xffffu) : (h | 0x8000u); key[gI * 8 + q] = (s0 + q <= t) ? k : 0u; }
;     }
.LBB0_3029:
	s_cmp_gt_i32 s43, 7
	s_cselect_b64 s[6:7], -1, 0
	s_cmp_lt_i32 s42, 8
	s_cselect_b64 s[48:49], -1, 0
	s_and_b64 s[0:1], s[48:49], s[6:7]
	s_andn2_b64 vcc, exec, s[0:1]
	s_cbranch_vccnz .LBB0_4695
	s_mov_b64 s[88:89], 0
	s_cmpk_lg_i32 s44, 0x100
	s_cbranch_scc1 .Lov_xl_done
	v_mov_b32_e32 v0, 0x20000
	ds_read_b32 v1, v0
	ds_read_b32 v2, v0 offset:4
	ds_read_b32 v0, v0 offset:12
	s_waitcnt lgkmcnt(0)
	v_readfirstlane_b32 s91, v1
	v_readfirstlane_b32 s92, v2
	v_readfirstlane_b32 s93, v0
	s_cmp_lg_u32 s91, 32
	s_cbranch_scc1 .Lov_xl_done
	s_cmp_lg_u32 s92, 8
	s_cbranch_scc1 .Lov_xl_done
	s_cmp_lt_u32 s93, 8
	s_cselect_b64 s[88:89], -1, 0
.Lov_xl_done:
	v_readlane_b32 s94, v255, 3
	s_and_b64 vcc, exec, s[88:89]
	s_cbranch_vccz .Lov_seq
	s_cmp_lt_u32 s94, 4
	s_cbranch_scc1 .Lp5a_begin
	s_branch .Lov_sel
.Lov_seq:
	s_cmp_eq_u32 s90, 1
	s_cbranch_scc0 .Lp5a_begin
.Lov_sel:
	v_readlane_b32 s0, v255, 0
	v_readlane_b32 s1, v255, 1
	s_lshl_b32 s0, s2, 3
	v_readlane_b32 s1, v255, 3
	s_add_i32 s50, s1, s0
	s_mov_b32 s95, s87
	s_and_b64 vcc, exec, s[88:89]
	s_cbranch_vccz .Lov_gw_done
	s_lshl_b32 s0, s2, 2
	s_add_i32 s50, s1, s0
	s_add_i32 s50, s50, -4
	s_lshr_b32 s95, s87, 1
.Lov_gw_done:
	s_cmpk_gt_i32 s50, 0x1fff
	s_waitcnt vmcnt(0)
	v_mbcnt_lo_u32_b32 v68, -1, 0
	v_mbcnt_hi_u32_b32 v68, -1, v68
	s_cbranch_scc1 .LBB0_4695
	s_add_u32 s0, s40, 0xe00000
	v_readlane_b32 s3, v255, 3
	s_addc_u32 s1, s41, 0
	s_lshl_b32 s4, s3, 9
	v_lshlrev_b32_e32 v70, 3, v68
	s_add_i32 s33, s4, 0
	v_ashrrev_i32_e32 v71, 31, v70
	s_add_i32 s6, s33, s4
	v_lshl_add_u64 v[0:1], v[70:71], 1, s[40:41]
	s_mov_b64 s[4:5], 0x17800000
	v_lshl_add_u64 v[72:73], v[0:1], 0, s[4:5]
	v_lshlrev_b32_e32 v1, 4, v68
	v_lshlrev_b32_e32 v74, 2, v68
	v_mov_b32_e32 v0, 0
	s_mov_b32 s3, 0
	s_add_i32 s45, s6, 0x1000
	v_or_b32_e32 v71, 2, v70
	v_or_b32_e32 v76, 3, v70
	v_or_b32_e32 v77, 4, v70
	v_or_b32_e32 v78, 5, v70
	v_or_b32_e32 v79, 6, v70
	v_or_b32_e32 v80, 7, v70
	v_add_u32_e32 v101, 0x604, v70
	v_add_u32_e32 v102, 0x605, v70
	v_add_u32_e32 v103, 0x606, v70
	v_add_u32_e32 v104, 0x607, v70
	v_add_u32_e32 v105, 0x800, v70
	v_add_u32_e32 v106, 0x801, v70
	v_add_u32_e32 v107, 0x802, v70
	v_add_u32_e32 v108, 0x803, v70
	v_add_u32_e32 v109, 0x804, v70
	v_add_u32_e32 v110, 0x805, v70
	v_add_u32_e32 v111, 0x806, v70
	v_add_u32_e32 v112, 0x807, v70
	v_add_u32_e32 v113, 0xa00, v70
	v_add_u32_e32 v114, 0xa01, v70
	v_add_u32_e32 v115, 0xa02, v70
	v_add_u32_e32 v116, 0xa03, v70
	v_add_u32_e32 v117, 0xa04, v70
	v_add_u32_e32 v118, 0xa05, v70
	v_add_u32_e32 v119, 0xa06, v70
	v_add_u32_e32 v120, 0xa07, v70
	v_add_u32_e32 v121, 0xc00, v70
	v_add_u32_e32 v122, 0xc01, v70
	v_add_u32_e32 v123, 0xc02, v70
	v_add_u32_e32 v124, 0xc03, v70
	v_add_u32_e32 v125, 0xc04, v70
	v_add_u32_e32 v126, 0xc05, v70
	v_add_u32_e32 v127, 0xc06, v70
	v_add_u32_e32 v128, 0xc07, v70
	v_add_u32_e32 v129, 0xe00, v70
	v_add_u32_e32 v130, 0xe01, v70
	v_add_u32_e32 v131, 0xe02, v70
	v_add_u32_e32 v132, 0xe03, v70
	v_add_u32_e32 v133, 0xe04, v70
	v_add_u32_e32 v134, 0xe05, v70
	v_add_u32_e32 v135, 0xe06, v70
	v_add_u32_e32 v136, 0xe07, v70
	v_add_u32_e32 v137, 0x1000, v70
	v_add_u32_e32 v138, 0x1001, v70
	v_add_u32_e32 v139, 0x1002, v70
	v_add_u32_e32 v140, 0x1003, v70
	v_add_u32_e32 v141, 0x1004, v70
	v_add_u32_e32 v142, 0x1005, v70
	v_add_u32_e32 v143, 0x1006, v70
	v_add_u32_e32 v144, 0x1007, v70
	v_add_u32_e32 v145, 0x1200, v70
	v_add_u32_e32 v146, 0x1201, v70
	v_add_u32_e32 v147, 0x1202, v70
	v_add_u32_e32 v148, 0x1203, v70
	v_add_u32_e32 v149, 0x1204, v70
	v_add_u32_e32 v150, 0x1205, v70
	v_add_u32_e32 v151, 0x1206, v70
	v_add_u32_e32 v152, 0x1207, v70
	v_add_u32_e32 v153, 0x1400, v70
	v_add_u32_e32 v154, 0x1401, v70
	v_add_u32_e32 v155, 0x1402, v70
	v_add_u32_e32 v156, 0x1403, v70
	v_add_u32_e32 v157, 0x1404, v70
	v_add_u32_e32 v158, 0x1405, v70
	v_add_u32_e32 v159, 0x1406, v70
	v_add_u32_e32 v160, 0x1407, v70
	v_add_u32_e32 v161, 0x1600, v70
	v_add_u32_e32 v162, 0x1601, v70
	v_add_u32_e32 v163, 0x1602, v70
	v_add_u32_e32 v164, 0x1603, v70
	v_add_u32_e32 v165, 0x1604, v70
	v_add_u32_e32 v166, 0x1605, v70
	v_add_u32_e32 v167, 0x1606, v70
	v_add_u32_e32 v168, 0x1607, v70
	v_add_u32_e32 v169, 0x1800, v70
	v_add_u32_e32 v170, 0x1801, v70
	v_add_u32_e32 v171, 0x1802, v70
	v_add_u32_e32 v172, 0x1803, v70
	v_add_u32_e32 v173, 0x1804, v70
	v_add_u32_e32 v174, 0x1805, v70
	v_add_u32_e32 v175, 0x1806, v70
	v_add_u32_e32 v176, 0x1807, v70
	v_add_u32_e32 v177, 0x1a00, v70
	v_add_u32_e32 v178, 0x1a01, v70
	v_add_u32_e32 v179, 0x1a02, v70
	v_add_u32_e32 v180, 0x1a03, v70
	v_add_u32_e32 v181, 0x1a04, v70
	v_add_u32_e32 v182, 0x1a05, v70
	v_add_u32_e32 v183, 0x1a06, v70
	v_add_u32_e32 v184, 0x1a07, v70
	v_add_u32_e32 v185, 0x1c00, v70
	v_add_u32_e32 v186, 0x1c01, v70
	v_add_u32_e32 v187, 0x1c02, v70
	v_add_u32_e32 v188, 0x1c03, v70
	v_add_u32_e32 v189, 0x1c04, v70
	v_add_u32_e32 v190, 0x1c05, v70
	v_add_u32_e32 v191, 0x1c06, v70
	v_add_u32_e32 v192, 0x1c07, v70
	v_add_u32_e32 v193, 0x1e00, v70
	v_add_u32_e32 v194, 0x1e01, v70
	v_add_u32_e32 v195, 0x1e02, v70
	v_add_u32_e32 v196, 0x1e03, v70
	v_add_u32_e32 v197, 0x1e04, v70
	v_add_u32_e32 v198, 0x1e05, v70
	v_add_u32_e32 v199, 0x1e06, v70
	v_add_u32_e32 v200, 0x1e07, v70
	v_ashrrev_i32_e32 v75, 31, v74
	v_ashrrev_i32_e32 v69, 31, v68
	v_add_u32_e32 v202, 64, v68
	v_add_u32_e32 v203, 0x80, v68
	v_add_u32_e32 v204, 0xc0, v68
	s_mov_b32 s46, 0xffff
	s_mov_b32 s47, 0x8000
	v_mov_b32_e32 v205, 1
	v_add_u32_e32 v206, s6, v1
	v_mov_b32_e32 v1, v0
	v_mov_b32_e32 v2, v0
	v_mov_b32_e32 v3, v0
	s_branch .LBB0_3033
.LBB0_3032:
	s_add_i32 s50, s50, s95
	s_cmpk_lt_i32 s50, 0x2000
	s_cbranch_scc0 .LBB0_4694

; #define LAS __attribute__((address_space(3)))
; __device__ __forceinline__ void attend_one(unsigned char* ws, LAS unsigned char* lds, int wave, int bb, int t, int kvh, int lane) {
;     asm volatile("" : "+v"(lane));
;     const int n = lane & 15, g = lane >> 4;
;     const bf16_t* Kb = (const bf16_t*)(ws + WS_DK) + (size_t)(bb * 4 + kvh) * 8192 * 128;
;     const bf16_t* Vb = (const bf16_t*)(ws + WS_DV) + (size_t)(bb * 4 + kvh) * 8192 * 128;
;     bf16_t* qrow = (bf16_t*)(ws + WS_DQ) + (size_t)(bb * 8192 + t) * 2048 + kvh * 512;
;     const unsigned short* ix = (const unsigned short*)(ws + WS_IDX) + (size_t)(bb * 8192 + t) * 256;
;     const int cnt = t < 255 ? t + 1 : 256;
;     LAS unsigned* li = (LAS unsigned*)(lds + wave * 1024);
;     { const u32x2 iw = *(const u32x2*)(ix + lane * 4); *(LAS u32x4*)(li + lane * 4) = (u32x4){(iw.x & 0xffffu) << 8, (iw.x >> 16) << 8, (iw.y & 0xffffu) << 8, (iw.y >> 16) << 8}; }
;     bf16x8 qf[4];
; #pragma unroll
;     for (int kk = 0; kk < 4; ++kk) { qf[kk] = (bf16x8){0, 0, 0, 0, 0, 0, 0, 0}; if (n < 4) qf[kk] = *(const bf16x8*)(qrow + n * 128 + kk * 32 + g * 8); }
.LBB0_4754:
	s_add_i32 s0, 0, 0x2000c
	v_mov_b32_e32 v0, s0
	ds_read_b32 v0, v0
	s_lshl_b32 s0, s2, 3
	s_add_i32 s4, 0, 0x20008
	v_readlane_b32 s1, v255, 3
	s_add_i32 s0, s1, s0
	s_waitcnt lgkmcnt(0)
	v_readfirstlane_b32 s1, v0
	v_mov_b32_e32 v0, s4
	ds_read_b32 v0, v0
	s_cmp_lt_i32 s0, 0x8000
	s_cselect_b64 s[4:5], -1, 0
	s_or_b64 s[4:5], s[12:13], s[4:5]
	s_mov_b32 s3, 0
	s_andn2_b64 vcc, exec, s[4:5]
	s_waitcnt lgkmcnt(0)
	v_readfirstlane_b32 s4, v0
	s_cbranch_vccnz .LBB0_4775
	v_readlane_b32 s7, v255, 3
	s_bfe_u32 s5, s1, 0x10002
	s_lshl_b32 s4, s4, 4
	s_lshl_b32 s6, s7, 1
	s_add_u32 s18, s40, 0x12800000
	s_addc_u32 s19, s41, 0
	s_add_u32 s20, s40, 0xd800000
	s_addc_u32 s21, s41, 0
	s_add_u32 s22, s40, 0xe00000
	s_addc_u32 s23, s41, 0
	s_lshl_b32 s7, s7, 10
	s_add_i32 s24, s7, 0
	s_add_u32 s25, s40, 0x11800000
	s_addc_u32 s26, s41, 0
	s_add_i32 s4, s4, s6
	s_mov_b64 s[100:101], exec
	s_lshl_b32 s98, s1, 6
	s_addk_i32 s98, 0x3c00
	s_add_u32 s98, s40, s98
	s_addc_u32 s99, s41, 0
	v_mov_b32_e32 v251, 0
	v_mov_b32_e32 v252, 1
	s_mov_b64 exec, 1
	global_atomic_add v250, v251, v252, s[98:99] sc0
	s_mov_b64 exec, s[100:101]
	s_waitcnt vmcnt(0)
	v_readfirstlane_b32 s100, v250
	s_bfe_u32 s101, s1, 0x10002
	s_lshl_b32 s27, s100, 1
	s_or_b32 s27, s27, s101
	v_mov_b32_e32 v161, 0
	s_mov_b32 s28, 0xff61b1e6
	s_mov_b32 s29, 0x5040100
	s_mov_b32 s30, 0x7060302
	v_mov_b32_e32 v165, 8
	v_mov_b32_e32 v166, 0xff61b1e6
	s_branch .LBB0_4757
.LBB0_4756:
	s_or_b64 exec, exec, s[4:5]
	s_add_i32 s0, s0, s87
	s_add_i32 s6, s3, 1
	s_cmp_lt_u32 s100, 0x1000
	s_cselect_b64 s[4:5], -1, 0
	s_cmp_lt_i32 s0, 0x8000
	v_cndmask_b32_e64 v0, 0, 1, s[4:5]
	s_cselect_b64 s[4:5], -1, 0
	v_cndmask_b32_e64 v1, 0, 1, s[4:5]
	v_cndmask_b32_e64 v0, v1, v0, s[12:13]
	v_and_b32_e32 v0, 1, v0
	v_cmp_eq_u32_e32 vcc, 1, v0
	s_bfe_u32 s101, s1, 0x10002
	s_lshl_b32 s27, s100, 1
	s_or_b32 s27, s27, s101
	s_mov_b32 s3, s6
	s_cbranch_vccz .LBB0_4775
.LBB0_4757:
	s_mov_b64 exec, 1
	global_atomic_add v250, v251, v252, s[98:99] sc0
	s_mov_b64 exec, -1
	s_ashr_i32 s6, s0, 2
	s_and_b64 s[4:5], s[12:13], exec
	s_cselect_b32 s4, s1, s0
	s_cselect_b32 s6, s27, s6
	s_and_b32 s7, s4, 3
	s_add_i32 s4, s6, 0x2000
	s_ashr_i32 s5, s4, 31
	s_lshl_b64 s[8:9], s[4:5], 12
	s_add_u32 s8, s20, s8
	s_addc_u32 s9, s21, s9
	s_lshl_b32 s14, s7, 10
	s_add_u32 s14, s8, s14
	v_mov_b32_e32 v167, v164
	s_addc_u32 s15, s9, 0
	s_lshl_b64 s[4:5], s[4:5], 9
	s_add_u32 s4, s22, s4
	v_lshlrev_b32_e32 v162, 2, v167
	s_addc_u32 s5, s23, s5
	v_ashrrev_i32_e32 v163, 31, v162
	v_lshl_add_u64 v[0:1], v[162:163], 1, s[4:5]
	global_load_dwordx2 v[6:7], v[0:1], off
	v_and_b32_e32 v18, 15, v167
	v_ashrrev_i32_e32 v168, 4, v167
	v_lshlrev_b32_e32 v160, 8, v18
	v_lshlrev_b32_e32 v4, 3, v168
	v_ashrrev_i32_e32 v5, 31, v4
	v_lshl_add_u64 v[8:9], s[14:15], 0, v[160:161]
	v_lshl_add_u64 v[16:17], v[4:5], 1, v[8:9]
	v_lshl_add_u32 v3, v167, 4, s24
	v_mov_b32_e32 v0, 0
	v_mov_b32_e32 v1, 0
	v_mov_b32_e32 v2, 0
	v_cmp_gt_u32_e32 vcc, 4, v18
	s_waitcnt vmcnt(0)
	v_readfirstlane_b32 s100, v250
	v_lshlrev_b32_e32 v4, 8, v6
	v_lshlrev_b32_sdwa v5, v165, v6 dst_sel:DWORD dst_unused:UNUSED_PAD src0_sel:DWORD src1_sel:WORD_1
	v_lshlrev_b32_e32 v6, 8, v7
	v_lshlrev_b32_sdwa v7, v165, v7 dst_sel:DWORD dst_unused:UNUSED_PAD src0_sel:DWORD src1_sel:WORD_1
	v_and_b32_e32 v4, 0xffff00, v4
	v_and_b32_e32 v6, 0xffff00, v6
	ds_write_b128 v3, v[4:7]
	v_mov_b32_e32 v3, 0
	s_and_saveexec_b64 s[4:5], vcc
	s_cbranch_execz .LBB0_4759
	global_load_dwordx4 v[0:3], v[16:17], off
